# gMLP gating matrices staged once per phase in LDS (ds_read fragments instead of 32 KB global loads per task)
# speedup vs baseline: 1.0153x; 1.0078x over previous
.LBB0_272:
	v_mov_b32_e32 v2, v1
	s_nop 0
	v_readfirstlane_b32 s0, v2
	v_and_b32_e32 v66, 63, v2
	s_ashr_i32 s12, s0, 6
	v_readlane_b32 s0, v252, 30
	s_add_i32 s35, s12, s0
	v_lshlrev_b32_e32 v3, 1, v66
	v_and_b32_e32 v4, 3, v2
	s_cmp_ge_i32 s35, s4
	v_and_b32_e32 v192, 15, v2
	v_and_or_b32 v193, v3, 24, v4
	s_cbranch_scc1 .LBB0_277
	v_lshrrev_b32_e32 v3, 1, v2
	v_and_b32_e32 v67, 24, v3
	v_readlane_b32 s0, v252, 53
	v_lshlrev_b32_e32 v194, 1, v67
	v_readlane_b32 s1, v252, 54
	v_and_b32_e32 v2, 48, v2
	s_lshl_b32 s5, s24, 10
	v_lshl_add_u64 v[42:43], s[0:1], 0, v[194:195]
	s_lshl_b32 s0, s12, 2
	v_readlane_b32 s1, v251, 59
	v_lshl_or_b32 v194, v192, 8, v2
	s_add_i32 s7, s1, s0
	v_readlane_b32 s0, v251, 61
	v_lshl_add_u64 v[44:45], s[94:95], 0, v[194:195]
	v_lshlrev_b32_e32 v194, 2, v192
	v_readlane_b32 s1, v251, 62
	v_or_b32_e32 v68, 32, v67
	v_or_b32_e32 v69, 64, v67
	v_or_b32_e32 v70, 0x60, v67
	s_lshl_b32 s6, s24, 17
	v_lshl_add_u64 v[46:47], s[0:1], 0, v[194:195]
	s_mov_b32 s8, s35
	v_lshrrev_b32_e32 v76, 4, v66
	v_lshlrev_b32_e32 v77, 1, v76
	v_sub_u32_e32 v78, v192, v77
	v_and_b32_e32 v79, 15, v78
	v_add_u32_e32 v78, 8, v78
	v_and_b32_e32 v78, 15, v78
	v_lshlrev_b32_e32 v80, 8, v76
	v_lshl_add_u32 v186, v79, 4, v80
	v_lshl_add_u32 v187, v78, 4, v80
	s_lshl_b32 s14, s92, 1
	s_and_b32 s14, s14, 6
	s_lshr_b32 s15, s12, 2
	s_or_b32 s14, s14, s15
	s_lshl_b32 s14, s14, 15
	s_lshl_b32 s20, s24, 18
	s_add_i32 s14, s14, s20
	s_and_b32 s20, s12, 3
	s_lshl_b32 s20, s20, 13
	s_add_i32 s14, s14, s20
	s_add_i32 s14, s14, 0x6400000
	s_add_u32 s22, s94, s14
	s_addc_u32 s23, s95, 0
	s_lshl_b32 s21, s12, 13
	s_mov_b32 m0, s21
	s_add_i32 s21, s21, 0x400
	global_load_lds_dwordx4 v186, s[22:23]
	s_add_u32 s22, s22, 0x400
	s_addc_u32 s23, s23, 0
	s_mov_b32 m0, s21
	s_add_i32 s21, s21, 0x400
	global_load_lds_dwordx4 v187, s[22:23]
	s_add_u32 s22, s22, 0x400
	s_addc_u32 s23, s23, 0
	s_mov_b32 m0, s21
	s_add_i32 s21, s21, 0x400
	global_load_lds_dwordx4 v186, s[22:23]
	s_add_u32 s22, s22, 0x400
	s_addc_u32 s23, s23, 0
	s_mov_b32 m0, s21
	s_add_i32 s21, s21, 0x400
	global_load_lds_dwordx4 v187, s[22:23]
	s_add_u32 s22, s22, 0x400
	s_addc_u32 s23, s23, 0
	s_mov_b32 m0, s21
	s_add_i32 s21, s21, 0x400
	global_load_lds_dwordx4 v186, s[22:23]
	s_add_u32 s22, s22, 0x400
	s_addc_u32 s23, s23, 0
	s_mov_b32 m0, s21
	s_add_i32 s21, s21, 0x400
	global_load_lds_dwordx4 v187, s[22:23]
	s_add_u32 s22, s22, 0x400
	s_addc_u32 s23, s23, 0
	s_mov_b32 m0, s21
	s_add_i32 s21, s21, 0x400
	global_load_lds_dwordx4 v186, s[22:23]
	s_add_u32 s22, s22, 0x400
	s_addc_u32 s23, s23, 0
	s_mov_b32 m0, s21
	s_add_i32 s21, s21, 0x400
	global_load_lds_dwordx4 v187, s[22:23]
	s_add_u32 s22, s22, 0x400
	s_addc_u32 s23, s23, 0
	v_and_b32_e32 v76, 7, v192
	v_lshlrev_b32_e32 v76, 1, v76
	v_lshrrev_b32_e32 v77, 4, v66
	v_add_u32_e32 v76, v76, v77
	v_lshlrev_b32_e32 v78, 8, v192
	s_lshl_b32 s20, s15, 15
	v_add_u32_e32 v78, s20, v78
	v_add_u32_e32 v79, 0, v76
	v_and_b32_e32 v79, 15, v79
	v_lshl_add_u32 v182, v79, 4, v78
	v_add_u32_e32 v79, 4, v76
	v_and_b32_e32 v79, 15, v79
	v_lshl_add_u32 v183, v79, 4, v78
	v_add_u32_e32 v79, 8, v76
	v_and_b32_e32 v79, 15, v79
	v_lshl_add_u32 v184, v79, 4, v78
	v_add_u32_e32 v79, 12, v76
	v_and_b32_e32 v79, 15, v79
	v_lshl_add_u32 v185, v79, 4, v78
	s_waitcnt vmcnt(0)
	s_barrier
.LBB0_274:
	s_bfe_u32 s0, s8, 0x30002
	s_lshl_b32 s1, s0, 14
	s_add_i32 s42, s6, s1
	s_and_b32 s1, s7, 0xffffff80
	v_or_b32_e32 v50, s1, v192
	s_lshl_b32 s0, s0, 7
	s_lshl_b32 s1, s8, 5
	v_lshl_add_u64 v[48:49], s[42:43], 1, v[44:45]
	s_add_i32 s42, s5, s0
	s_lshl_b32 s0, s8, 2
	s_and_b32 s9, s1, 0x3e0
	s_and_b32 s0, s0, 0xffffff80
	v_or_b32_e32 v22, s9, v193
	v_or_b32_e32 v2, s0, v67
	v_or_b32_e32 v194, s5, v22
	v_readlane_b32 s52, v252, 12
	v_ashrrev_i32_e32 v3, 31, v2
	v_lshlrev_b64 v[4:5], 2, v[194:195]
	v_readlane_b32 s53, v252, 13
	v_readlane_b32 s54, v252, 14
	v_readlane_b32 s55, v252, 15
	s_ashr_i32 s1, s0, 31
	v_lshl_add_u64 v[2:3], v[2:3], 3, s[2:3]
	v_lshl_add_u64 v[62:63], s[52:53], 0, v[4:5]
	v_lshl_add_u64 v[64:65], s[54:55], 0, v[4:5]
	v_mul_u32_u24_e32 v4, 0x4800, v22
	global_load_dwordx4 v[76:79], v[2:3], off
	global_load_dwordx4 v[80:83], v[2:3], off offset:16
	global_load_dwordx4 v[84:87], v[2:3], off offset:32
	global_load_dwordx4 v[88:91], v[2:3], off offset:48
	global_load_dwordx4 v[92:95], v[2:3], off offset:256
	global_load_dwordx4 v[96:99], v[2:3], off offset:272
	global_load_dwordx4 v[100:103], v[2:3], off offset:288
	global_load_dwordx4 v[104:107], v[2:3], off offset:304
	global_load_dwordx4 v[108:111], v[2:3], off offset:512
	global_load_dwordx4 v[112:115], v[2:3], off offset:528
	global_load_dwordx4 v[116:119], v[2:3], off offset:544
	global_load_dwordx4 v[120:123], v[2:3], off offset:560
	global_load_dwordx4 v[124:127], v[2:3], off offset:768
	global_load_dwordx4 v[128:131], v[2:3], off offset:784
	global_load_dwordx4 v[132:135], v[2:3], off offset:800
	global_load_dwordx4 v[136:139], v[2:3], off offset:816
	v_lshl_add_u64 v[2:3], s[0:1], 1, v[42:43]
	v_lshlrev_b32_e32 v194, 1, v4
	v_lshl_add_u64 v[60:61], v[2:3], 0, v[194:195]
	s_mov_b32 s1, 0x24000
	s_mov_b64 s[10:11], 0x24000
	v_lshl_add_u64 v[54:55], v[60:61], 0, s[10:11]
	v_lshl_add_u64 v[52:53], s[42:43], 2, v[46:47]
	global_load_dwordx4 v[140:143], v[60:61], off
	global_load_dwordx4 v[144:147], v[60:61], off offset:64
	global_load_dwordx4 v[148:151], v[60:61], off offset:128
	global_load_dwordx4 v[152:155], v[60:61], off offset:192
	global_load_dwordx4 v[156:159], v[54:55], off
	global_load_dwordx4 v[160:163], v[54:55], off offset:64
	global_load_dwordx4 v[164:167], v[54:55], off offset:128
	global_load_dwordx4 v[168:171], v[54:55], off offset:192
	global_load_dword v172, v[62:63], off
	global_load_dword v173, v[64:65], off
	global_load_dword v174, v[62:63], off offset:16
	global_load_dword v175, v[64:65], off offset:16
	v_readlane_b32 s56, v252, 16
	v_readlane_b32 s57, v252, 17
	v_readlane_b32 s58, v252, 18
	v_readlane_b32 s59, v252, 19
	v_readlane_b32 s60, v252, 20
	v_readlane_b32 s61, v252, 21
	v_readlane_b32 s62, v252, 22
	v_readlane_b32 s63, v252, 23
	v_readlane_b32 s64, v252, 24
	v_readlane_b32 s65, v252, 25
	v_readlane_b32 s66, v252, 26
	v_readlane_b32 s67, v252, 27
	v_readlane_b32 s0, v251, 35
	v_readlane_b32 s1, v251, 36
	s_waitcnt vmcnt(0)
	v_lshlrev_b32_e32 v34, 16, v140
	v_and_b32_e32 v35, 0xffff0000, v140
	v_sub_f32_e32 v34, v34, v76
	v_sub_f32_e32 v35, v35, v78
	v_mul_f32_e32 v34, v77, v34
	v_mul_f32_e32 v35, v79, v35
	v_fma_f32 v34, v172, v34, v173
	v_fma_f32 v35, v172, v35, v173
	v_cvt_pk_bf16_f32 v2, v34, v35
	v_lshlrev_b32_e32 v34, 16, v141
	v_and_b32_e32 v35, 0xffff0000, v141
	v_sub_f32_e32 v34, v34, v80
	v_sub_f32_e32 v35, v35, v82
	v_mul_f32_e32 v34, v81, v34
	v_mul_f32_e32 v35, v83, v35
	v_fma_f32 v34, v172, v34, v173
	v_fma_f32 v35, v172, v35, v173
	v_cvt_pk_bf16_f32 v3, v34, v35
	v_lshlrev_b32_e32 v34, 16, v142
	v_and_b32_e32 v35, 0xffff0000, v142
	v_sub_f32_e32 v34, v34, v84
	v_sub_f32_e32 v35, v35, v86
	v_mul_f32_e32 v34, v85, v34
	v_mul_f32_e32 v35, v87, v35
	v_fma_f32 v34, v172, v34, v173
	v_fma_f32 v35, v172, v35, v173
	v_cvt_pk_bf16_f32 v4, v34, v35
	v_lshlrev_b32_e32 v34, 16, v143
	v_and_b32_e32 v35, 0xffff0000, v143
	v_sub_f32_e32 v34, v34, v88
	v_sub_f32_e32 v35, v35, v90
	v_mul_f32_e32 v34, v89, v34
	v_mul_f32_e32 v35, v91, v35
	v_fma_f32 v34, v172, v34, v173
	v_fma_f32 v35, v172, v35, v173
	v_cvt_pk_bf16_f32 v5, v34, v35
	v_lshlrev_b32_e32 v34, 16, v156
	v_and_b32_e32 v35, 0xffff0000, v156
	v_sub_f32_e32 v34, v34, v76
	v_sub_f32_e32 v35, v35, v78
	v_mul_f32_e32 v34, v77, v34
	v_mul_f32_e32 v35, v79, v35
	v_fma_f32 v34, v174, v34, v175
	v_fma_f32 v35, v174, v35, v175
	v_cvt_pk_bf16_f32 v6, v34, v35
	v_lshlrev_b32_e32 v34, 16, v157
	v_and_b32_e32 v35, 0xffff0000, v157
	v_sub_f32_e32 v34, v34, v80
	v_sub_f32_e32 v35, v35, v82
	v_mul_f32_e32 v34, v81, v34
	v_mul_f32_e32 v35, v83, v35
	v_fma_f32 v34, v174, v34, v175
	v_fma_f32 v35, v174, v35, v175
	v_cvt_pk_bf16_f32 v7, v34, v35
	v_lshlrev_b32_e32 v34, 16, v158
	v_and_b32_e32 v35, 0xffff0000, v158
	v_sub_f32_e32 v34, v34, v84
	v_sub_f32_e32 v35, v35, v86
	v_mul_f32_e32 v34, v85, v34
	v_mul_f32_e32 v35, v87, v35
	v_fma_f32 v34, v174, v34, v175
	v_fma_f32 v35, v174, v35, v175
	v_cvt_pk_bf16_f32 v8, v34, v35
	v_lshlrev_b32_e32 v34, 16, v159
	v_and_b32_e32 v35, 0xffff0000, v159
	v_sub_f32_e32 v34, v34, v88
	v_sub_f32_e32 v35, v35, v90
	v_mul_f32_e32 v34, v89, v34
	v_mul_f32_e32 v35, v91, v35
	v_fma_f32 v34, v174, v34, v175
	v_fma_f32 v35, v174, v35, v175
	v_cvt_pk_bf16_f32 v9, v34, v35
	v_lshlrev_b32_e32 v34, 16, v144
	v_and_b32_e32 v35, 0xffff0000, v144
	v_sub_f32_e32 v34, v34, v92
	v_sub_f32_e32 v35, v35, v94
	v_mul_f32_e32 v34, v93, v34
	v_mul_f32_e32 v35, v95, v35
	v_fma_f32 v34, v172, v34, v173
	v_fma_f32 v35, v172, v35, v173
	v_cvt_pk_bf16_f32 v10, v34, v35
	v_lshlrev_b32_e32 v34, 16, v145
	v_and_b32_e32 v35, 0xffff0000, v145
	v_sub_f32_e32 v34, v34, v96
	v_sub_f32_e32 v35, v35, v98
	v_mul_f32_e32 v34, v97, v34
	v_mul_f32_e32 v35, v99, v35
	v_fma_f32 v34, v172, v34, v173
	v_fma_f32 v35, v172, v35, v173
	v_cvt_pk_bf16_f32 v11, v34, v35
	v_lshlrev_b32_e32 v34, 16, v146
	v_and_b32_e32 v35, 0xffff0000, v146
	v_sub_f32_e32 v34, v34, v100
	v_sub_f32_e32 v35, v35, v102
	v_mul_f32_e32 v34, v101, v34
	v_mul_f32_e32 v35, v103, v35
	v_fma_f32 v34, v172, v34, v173
	v_fma_f32 v35, v172, v35, v173
	v_cvt_pk_bf16_f32 v12, v34, v35
	v_lshlrev_b32_e32 v34, 16, v147
	v_and_b32_e32 v35, 0xffff0000, v147
	v_sub_f32_e32 v34, v34, v104
	v_sub_f32_e32 v35, v35, v106
	v_mul_f32_e32 v34, v105, v34
	v_mul_f32_e32 v35, v107, v35
	v_fma_f32 v34, v172, v34, v173
	v_fma_f32 v35, v172, v35, v173
	v_cvt_pk_bf16_f32 v13, v34, v35
	v_lshlrev_b32_e32 v34, 16, v160
	v_and_b32_e32 v35, 0xffff0000, v160
	v_sub_f32_e32 v34, v34, v92
	v_sub_f32_e32 v35, v35, v94
	v_mul_f32_e32 v34, v93, v34
	v_mul_f32_e32 v35, v95, v35
	v_fma_f32 v34, v174, v34, v175
	v_fma_f32 v35, v174, v35, v175
	v_cvt_pk_bf16_f32 v14, v34, v35
	v_lshlrev_b32_e32 v34, 16, v161
	v_and_b32_e32 v35, 0xffff0000, v161
	v_sub_f32_e32 v34, v34, v96
	v_sub_f32_e32 v35, v35, v98
	v_mul_f32_e32 v34, v97, v34
	v_mul_f32_e32 v35, v99, v35
	v_fma_f32 v34, v174, v34, v175
	v_fma_f32 v35, v174, v35, v175
	v_cvt_pk_bf16_f32 v15, v34, v35
	v_lshlrev_b32_e32 v34, 16, v162
	v_and_b32_e32 v35, 0xffff0000, v162
	v_sub_f32_e32 v34, v34, v100
	v_sub_f32_e32 v35, v35, v102
	v_mul_f32_e32 v34, v101, v34
	v_mul_f32_e32 v35, v103, v35
	v_fma_f32 v34, v174, v34, v175
	v_fma_f32 v35, v174, v35, v175
	v_cvt_pk_bf16_f32 v16, v34, v35
	v_lshlrev_b32_e32 v34, 16, v163
	v_and_b32_e32 v35, 0xffff0000, v163
	v_sub_f32_e32 v34, v34, v104
	v_sub_f32_e32 v35, v35, v106
	v_mul_f32_e32 v34, v105, v34
	v_mul_f32_e32 v35, v107, v35
	v_fma_f32 v34, v174, v34, v175
	v_fma_f32 v35, v174, v35, v175
	v_cvt_pk_bf16_f32 v17, v34, v35
	v_lshlrev_b32_e32 v34, 16, v148
	v_and_b32_e32 v35, 0xffff0000, v148
	v_sub_f32_e32 v34, v34, v108
	v_sub_f32_e32 v35, v35, v110
	v_mul_f32_e32 v34, v109, v34
	v_mul_f32_e32 v35, v111, v35
	v_fma_f32 v34, v172, v34, v173
	v_fma_f32 v35, v172, v35, v173
	v_cvt_pk_bf16_f32 v18, v34, v35
	v_lshlrev_b32_e32 v34, 16, v149
	v_and_b32_e32 v35, 0xffff0000, v149
	v_sub_f32_e32 v34, v34, v112
	v_sub_f32_e32 v35, v35, v114
	v_mul_f32_e32 v34, v113, v34
	v_mul_f32_e32 v35, v115, v35
	v_fma_f32 v34, v172, v34, v173
	v_fma_f32 v35, v172, v35, v173
	v_cvt_pk_bf16_f32 v19, v34, v35
	v_lshlrev_b32_e32 v34, 16, v150
	v_and_b32_e32 v35, 0xffff0000, v150
	v_sub_f32_e32 v34, v34, v116
	v_sub_f32_e32 v35, v35, v118
	v_mul_f32_e32 v34, v117, v34
	v_mul_f32_e32 v35, v119, v35
	v_fma_f32 v34, v172, v34, v173
	v_fma_f32 v35, v172, v35, v173
	v_cvt_pk_bf16_f32 v20, v34, v35
	v_lshlrev_b32_e32 v34, 16, v151
	v_and_b32_e32 v35, 0xffff0000, v151
	v_sub_f32_e32 v34, v34, v120
	v_sub_f32_e32 v35, v35, v122
	v_mul_f32_e32 v34, v121, v34
	v_mul_f32_e32 v35, v123, v35
	v_fma_f32 v34, v172, v34, v173
	v_fma_f32 v35, v172, v35, v173
	v_cvt_pk_bf16_f32 v21, v34, v35
	v_lshlrev_b32_e32 v34, 16, v164
	v_and_b32_e32 v35, 0xffff0000, v164
	v_sub_f32_e32 v34, v34, v108
	v_sub_f32_e32 v35, v35, v110
	v_mul_f32_e32 v34, v109, v34
	v_mul_f32_e32 v35, v111, v35
	v_fma_f32 v34, v174, v34, v175
	v_fma_f32 v35, v174, v35, v175
	v_cvt_pk_bf16_f32 v22, v34, v35
	v_lshlrev_b32_e32 v34, 16, v165
	v_and_b32_e32 v35, 0xffff0000, v165
	v_sub_f32_e32 v34, v34, v112
	v_sub_f32_e32 v35, v35, v114
	v_mul_f32_e32 v34, v113, v34
	v_mul_f32_e32 v35, v115, v35
	v_fma_f32 v34, v174, v34, v175
	v_fma_f32 v35, v174, v35, v175
	v_cvt_pk_bf16_f32 v23, v34, v35
	v_lshlrev_b32_e32 v34, 16, v166
	v_and_b32_e32 v35, 0xffff0000, v166
	v_sub_f32_e32 v34, v34, v116
	v_sub_f32_e32 v35, v35, v118
	v_mul_f32_e32 v34, v117, v34
	v_mul_f32_e32 v35, v119, v35
	v_fma_f32 v34, v174, v34, v175
	v_fma_f32 v35, v174, v35, v175
	v_cvt_pk_bf16_f32 v24, v34, v35
	v_lshlrev_b32_e32 v34, 16, v167
	v_and_b32_e32 v35, 0xffff0000, v167
	v_sub_f32_e32 v34, v34, v120
	v_sub_f32_e32 v35, v35, v122
	v_mul_f32_e32 v34, v121, v34
	v_mul_f32_e32 v35, v123, v35
	v_fma_f32 v34, v174, v34, v175
	v_fma_f32 v35, v174, v35, v175
	v_cvt_pk_bf16_f32 v25, v34, v35
	v_lshlrev_b32_e32 v34, 16, v152
	v_and_b32_e32 v35, 0xffff0000, v152
	v_sub_f32_e32 v34, v34, v124
	v_sub_f32_e32 v35, v35, v126
	v_mul_f32_e32 v34, v125, v34
	v_mul_f32_e32 v35, v127, v35
	v_fma_f32 v34, v172, v34, v173
	v_fma_f32 v35, v172, v35, v173
	v_cvt_pk_bf16_f32 v26, v34, v35
	v_lshlrev_b32_e32 v34, 16, v153
	v_and_b32_e32 v35, 0xffff0000, v153
	v_sub_f32_e32 v34, v34, v128
	v_sub_f32_e32 v35, v35, v130
	v_mul_f32_e32 v34, v129, v34
	v_mul_f32_e32 v35, v131, v35
	v_fma_f32 v34, v172, v34, v173
	v_fma_f32 v35, v172, v35, v173
	v_cvt_pk_bf16_f32 v27, v34, v35
	v_lshlrev_b32_e32 v34, 16, v154
	v_and_b32_e32 v35, 0xffff0000, v154
	v_sub_f32_e32 v34, v34, v132
	v_sub_f32_e32 v35, v35, v134
	v_mul_f32_e32 v34, v133, v34
	v_mul_f32_e32 v35, v135, v35
	v_fma_f32 v34, v172, v34, v173
	v_fma_f32 v35, v172, v35, v173
	v_cvt_pk_bf16_f32 v28, v34, v35
	v_lshlrev_b32_e32 v34, 16, v155
	v_and_b32_e32 v35, 0xffff0000, v155
	v_sub_f32_e32 v34, v34, v136
	v_sub_f32_e32 v35, v35, v138
	v_mul_f32_e32 v34, v137, v34
	v_mul_f32_e32 v35, v139, v35
	v_fma_f32 v34, v172, v34, v173
	v_fma_f32 v35, v172, v35, v173
	v_cvt_pk_bf16_f32 v29, v34, v35
	v_lshlrev_b32_e32 v34, 16, v168
	v_and_b32_e32 v35, 0xffff0000, v168
	v_sub_f32_e32 v34, v34, v124
	v_sub_f32_e32 v35, v35, v126
	v_mul_f32_e32 v34, v125, v34
	v_mul_f32_e32 v35, v127, v35
	v_fma_f32 v34, v174, v34, v175
	v_fma_f32 v35, v174, v35, v175
	v_cvt_pk_bf16_f32 v30, v34, v35
	v_lshlrev_b32_e32 v34, 16, v169
	v_and_b32_e32 v35, 0xffff0000, v169
	v_sub_f32_e32 v34, v34, v128
	v_sub_f32_e32 v35, v35, v130
	v_mul_f32_e32 v34, v129, v34
	v_mul_f32_e32 v35, v131, v35
	v_fma_f32 v34, v174, v34, v175
	v_fma_f32 v35, v174, v35, v175
	v_cvt_pk_bf16_f32 v31, v34, v35
	v_lshlrev_b32_e32 v34, 16, v170
	v_and_b32_e32 v35, 0xffff0000, v170
	v_sub_f32_e32 v34, v34, v132
	v_sub_f32_e32 v35, v35, v134
	v_mul_f32_e32 v34, v133, v34
	v_mul_f32_e32 v35, v135, v35
	v_fma_f32 v34, v174, v34, v175
	v_fma_f32 v35, v174, v35, v175
	v_cvt_pk_bf16_f32 v32, v34, v35
	v_lshlrev_b32_e32 v34, 16, v171
	v_and_b32_e32 v35, 0xffff0000, v171
	v_sub_f32_e32 v34, v34, v136
	v_sub_f32_e32 v35, v35, v138
	v_mul_f32_e32 v34, v137, v34
	v_mul_f32_e32 v35, v139, v35
	v_fma_f32 v34, v174, v34, v175
	v_fma_f32 v35, v174, v35, v175
	v_cvt_pk_bf16_f32 v33, v34, v35
	v_or_b32_e32 v34, s9, v67
	v_lshlrev_b32_e32 v194, 1, v34
	v_lshl_add_u64 v[54:55], s[0:1], 0, v[194:195]
	v_lshl_add_u64 v[56:57], s[50:51], 0, v[194:195]
	global_load_dword v172, v[52:53], off offset:-64
	v_mov_b32_e32 v180, v50
	v_mad_i64_i32 v[176:177], s[10:11], v180, s37, v[56:57]
	global_load_dwordx4 v[140:143], v[176:177], off
	global_load_dwordx4 v[156:159], v[176:177], off offset:2048
	global_load_dword v173, v[52:53], off offset:0
	v_add_u32_e32 v180, 16, v50
	v_mad_i64_i32 v[176:177], s[10:11], v180, s37, v[56:57]
	global_load_dwordx4 v[144:147], v[176:177], off
	global_load_dwordx4 v[160:163], v[176:177], off offset:2048
	global_load_dword v174, v[52:53], off offset:64
	v_add_u32_e32 v180, 32, v50
	v_mad_i64_i32 v[176:177], s[10:11], v180, s37, v[56:57]
	global_load_dwordx4 v[148:151], v[176:177], off
	global_load_dwordx4 v[164:167], v[176:177], off offset:2048
	global_load_dword v175, v[52:53], off offset:128
	v_add_u32_e32 v180, 48, v50
	v_mad_i64_i32 v[176:177], s[10:11], v180, s37, v[56:57]
	global_load_dwordx4 v[152:155], v[176:177], off
	global_load_dwordx4 v[168:171], v[176:177], off offset:2048
	ds_read_b128 v[76:79], v182
	ds_read_b128 v[80:83], v183
	ds_read_b128 v[84:87], v184
	ds_read_b128 v[88:91], v185
	ds_read_b128 v[92:95], v182 offset:4096
	ds_read_b128 v[96:99], v183 offset:4096
	ds_read_b128 v[100:103], v184 offset:4096
	ds_read_b128 v[104:107], v185 offset:4096
	ds_read_b128 v[108:111], v182 offset:8192
	ds_read_b128 v[112:115], v183 offset:8192
	ds_read_b128 v[116:119], v184 offset:8192
	ds_read_b128 v[120:123], v185 offset:8192
	ds_read_b128 v[124:127], v182 offset:12288
	ds_read_b128 v[128:131], v183 offset:12288
	ds_read_b128 v[132:135], v184 offset:12288
	ds_read_b128 v[136:139], v185 offset:12288
	s_waitcnt vmcnt(9) lgkmcnt(12)
	v_mfma_f32_16x16x32_bf16 v[38:41], v[2:5], v[76:79], 0
	v_mfma_f32_16x16x32_bf16 v[34:37], v[6:9], v[76:79], 0
	v_mfma_f32_16x16x32_bf16 v[38:41], v[10:13], v[80:83], v[38:41]
	v_mfma_f32_16x16x32_bf16 v[34:37], v[14:17], v[80:83], v[34:37]
	v_mfma_f32_16x16x32_bf16 v[38:41], v[18:21], v[84:87], v[38:41]
	v_mfma_f32_16x16x32_bf16 v[34:37], v[22:25], v[84:87], v[34:37]
	v_mfma_f32_16x16x32_bf16 v[38:41], v[26:29], v[88:91], v[38:41]
	v_mfma_f32_16x16x32_bf16 v[34:37], v[30:33], v[88:91], v[34:37]
	v_mov_b32_e32 v180, v50
	v_ashrrev_i32_e32 v181, 31, v180
	v_lshlrev_b64 v[178:179], 11, v[180:181]
	v_lshl_add_u64 v[178:179], v[54:55], 0, v[178:179]
	s_nop 7
	v_add_f32_e32 v62, v38, v172
	v_add_f32_e32 v63, v39, v172
	v_lshlrev_b32_e32 v64, 16, v140
	v_and_b32_e32 v65, 0xffff0000, v140
	v_mul_f32_e32 v62, v62, v64
	v_mul_f32_e32 v63, v63, v65
	v_lshlrev_b32_e32 v64, 16, v156
	v_and_b32_e32 v65, 0xffff0000, v156
	v_mul_f32_e32 v62, v62, v64
	v_mul_f32_e32 v63, v63, v65
	v_cvt_pk_bf16_f32 v58, v62, v63
	v_add_f32_e32 v62, v40, v172
	v_add_f32_e32 v63, v41, v172
	v_lshlrev_b32_e32 v64, 16, v141
	v_and_b32_e32 v65, 0xffff0000, v141
	v_mul_f32_e32 v62, v62, v64
	v_mul_f32_e32 v63, v63, v65
	v_lshlrev_b32_e32 v64, 16, v157
	v_and_b32_e32 v65, 0xffff0000, v157
	v_mul_f32_e32 v62, v62, v64
	v_mul_f32_e32 v63, v63, v65
	v_cvt_pk_bf16_f32 v59, v62, v63
	v_add_f32_e32 v62, v34, v172
	v_add_f32_e32 v63, v35, v172
	v_lshlrev_b32_e32 v64, 16, v142
	v_and_b32_e32 v65, 0xffff0000, v142
	v_mul_f32_e32 v62, v62, v64
	v_mul_f32_e32 v63, v63, v65
	v_lshlrev_b32_e32 v64, 16, v158
	v_and_b32_e32 v65, 0xffff0000, v158
	v_mul_f32_e32 v62, v62, v64
	v_mul_f32_e32 v63, v63, v65
	v_cvt_pk_bf16_f32 v60, v62, v63
	v_add_f32_e32 v62, v36, v172
	v_add_f32_e32 v63, v37, v172
	v_lshlrev_b32_e32 v64, 16, v143
	v_and_b32_e32 v65, 0xffff0000, v143
	v_mul_f32_e32 v62, v62, v64
	v_mul_f32_e32 v63, v63, v65
	v_lshlrev_b32_e32 v64, 16, v159
	v_and_b32_e32 v65, 0xffff0000, v159
	v_mul_f32_e32 v62, v62, v64
	v_mul_f32_e32 v63, v63, v65
	v_cvt_pk_bf16_f32 v61, v62, v63
	global_store_dwordx4 v[178:179], v[58:61], off
	s_waitcnt vmcnt(7) lgkmcnt(8)
	v_mfma_f32_16x16x32_bf16 v[38:41], v[2:5], v[92:95], 0
	v_mfma_f32_16x16x32_bf16 v[34:37], v[6:9], v[92:95], 0
	v_mfma_f32_16x16x32_bf16 v[38:41], v[10:13], v[96:99], v[38:41]
	v_mfma_f32_16x16x32_bf16 v[34:37], v[14:17], v[96:99], v[34:37]
	v_mfma_f32_16x16x32_bf16 v[38:41], v[18:21], v[100:103], v[38:41]
	v_mfma_f32_16x16x32_bf16 v[34:37], v[22:25], v[100:103], v[34:37]
	v_mfma_f32_16x16x32_bf16 v[38:41], v[26:29], v[104:107], v[38:41]
	v_mfma_f32_16x16x32_bf16 v[34:37], v[30:33], v[104:107], v[34:37]
	v_add_u32_e32 v180, 16, v50
	v_ashrrev_i32_e32 v181, 31, v180
	v_lshlrev_b64 v[178:179], 11, v[180:181]
	v_lshl_add_u64 v[178:179], v[54:55], 0, v[178:179]
	s_nop 7
	v_add_f32_e32 v62, v38, v173
	v_add_f32_e32 v63, v39, v173
	v_lshlrev_b32_e32 v64, 16, v144
	v_and_b32_e32 v65, 0xffff0000, v144
	v_mul_f32_e32 v62, v62, v64
	v_mul_f32_e32 v63, v63, v65
	v_lshlrev_b32_e32 v64, 16, v160
	v_and_b32_e32 v65, 0xffff0000, v160
	v_mul_f32_e32 v62, v62, v64
	v_mul_f32_e32 v63, v63, v65
	v_cvt_pk_bf16_f32 v58, v62, v63
	v_add_f32_e32 v62, v40, v173
	v_add_f32_e32 v63, v41, v173
	v_lshlrev_b32_e32 v64, 16, v145
	v_and_b32_e32 v65, 0xffff0000, v145
	v_mul_f32_e32 v62, v62, v64
	v_mul_f32_e32 v63, v63, v65
	v_lshlrev_b32_e32 v64, 16, v161
	v_and_b32_e32 v65, 0xffff0000, v161
	v_mul_f32_e32 v62, v62, v64
	v_mul_f32_e32 v63, v63, v65
	v_cvt_pk_bf16_f32 v59, v62, v63
	v_add_f32_e32 v62, v34, v173
	v_add_f32_e32 v63, v35, v173
	v_lshlrev_b32_e32 v64, 16, v146
	v_and_b32_e32 v65, 0xffff0000, v146
	v_mul_f32_e32 v62, v62, v64
	v_mul_f32_e32 v63, v63, v65
	v_lshlrev_b32_e32 v64, 16, v162
	v_and_b32_e32 v65, 0xffff0000, v162
	v_mul_f32_e32 v62, v62, v64
	v_mul_f32_e32 v63, v63, v65
	v_cvt_pk_bf16_f32 v60, v62, v63
	v_add_f32_e32 v62, v36, v173
	v_add_f32_e32 v63, v37, v173
	v_lshlrev_b32_e32 v64, 16, v147
	v_and_b32_e32 v65, 0xffff0000, v147
	v_mul_f32_e32 v62, v62, v64
	v_mul_f32_e32 v63, v63, v65
	v_lshlrev_b32_e32 v64, 16, v163
	v_and_b32_e32 v65, 0xffff0000, v163
	v_mul_f32_e32 v62, v62, v64
	v_mul_f32_e32 v63, v63, v65
	v_cvt_pk_bf16_f32 v61, v62, v63
	global_store_dwordx4 v[178:179], v[58:61], off
	s_waitcnt vmcnt(5) lgkmcnt(4)
	v_mfma_f32_16x16x32_bf16 v[38:41], v[2:5], v[108:111], 0
	v_mfma_f32_16x16x32_bf16 v[34:37], v[6:9], v[108:111], 0
	v_mfma_f32_16x16x32_bf16 v[38:41], v[10:13], v[112:115], v[38:41]
	v_mfma_f32_16x16x32_bf16 v[34:37], v[14:17], v[112:115], v[34:37]
	v_mfma_f32_16x16x32_bf16 v[38:41], v[18:21], v[116:119], v[38:41]
	v_mfma_f32_16x16x32_bf16 v[34:37], v[22:25], v[116:119], v[34:37]
	v_mfma_f32_16x16x32_bf16 v[38:41], v[26:29], v[120:123], v[38:41]
	v_mfma_f32_16x16x32_bf16 v[34:37], v[30:33], v[120:123], v[34:37]
	v_add_u32_e32 v180, 32, v50
	v_ashrrev_i32_e32 v181, 31, v180
	v_lshlrev_b64 v[178:179], 11, v[180:181]
	v_lshl_add_u64 v[178:179], v[54:55], 0, v[178:179]
	s_nop 7
	v_add_f32_e32 v62, v38, v174
	v_add_f32_e32 v63, v39, v174
	v_lshlrev_b32_e32 v64, 16, v148
	v_and_b32_e32 v65, 0xffff0000, v148
	v_mul_f32_e32 v62, v62, v64
	v_mul_f32_e32 v63, v63, v65
	v_lshlrev_b32_e32 v64, 16, v164
	v_and_b32_e32 v65, 0xffff0000, v164
	v_mul_f32_e32 v62, v62, v64
	v_mul_f32_e32 v63, v63, v65
	v_cvt_pk_bf16_f32 v58, v62, v63
	v_add_f32_e32 v62, v40, v174
	v_add_f32_e32 v63, v41, v174
	v_lshlrev_b32_e32 v64, 16, v149
	v_and_b32_e32 v65, 0xffff0000, v149
	v_mul_f32_e32 v62, v62, v64
	v_mul_f32_e32 v63, v63, v65
	v_lshlrev_b32_e32 v64, 16, v165
	v_and_b32_e32 v65, 0xffff0000, v165
	v_mul_f32_e32 v62, v62, v64
	v_mul_f32_e32 v63, v63, v65
	v_cvt_pk_bf16_f32 v59, v62, v63
	v_add_f32_e32 v62, v34, v174
	v_add_f32_e32 v63, v35, v174
	v_lshlrev_b32_e32 v64, 16, v150
	v_and_b32_e32 v65, 0xffff0000, v150
	v_mul_f32_e32 v62, v62, v64
	v_mul_f32_e32 v63, v63, v65
	v_lshlrev_b32_e32 v64, 16, v166
	v_and_b32_e32 v65, 0xffff0000, v166
	v_mul_f32_e32 v62, v62, v64
	v_mul_f32_e32 v63, v63, v65
	v_cvt_pk_bf16_f32 v60, v62, v63
	v_add_f32_e32 v62, v36, v174
	v_add_f32_e32 v63, v37, v174
	v_lshlrev_b32_e32 v64, 16, v151
	v_and_b32_e32 v65, 0xffff0000, v151
	v_mul_f32_e32 v62, v62, v64
	v_mul_f32_e32 v63, v63, v65
	v_lshlrev_b32_e32 v64, 16, v167
	v_and_b32_e32 v65, 0xffff0000, v167
	v_mul_f32_e32 v62, v62, v64
	v_mul_f32_e32 v63, v63, v65
	v_cvt_pk_bf16_f32 v61, v62, v63
	global_store_dwordx4 v[178:179], v[58:61], off
	s_waitcnt vmcnt(3) lgkmcnt(0)
	v_mfma_f32_16x16x32_bf16 v[38:41], v[2:5], v[124:127], 0
	v_mfma_f32_16x16x32_bf16 v[34:37], v[6:9], v[124:127], 0
	v_mfma_f32_16x16x32_bf16 v[38:41], v[10:13], v[128:131], v[38:41]
	v_mfma_f32_16x16x32_bf16 v[34:37], v[14:17], v[128:131], v[34:37]
	v_mfma_f32_16x16x32_bf16 v[38:41], v[18:21], v[132:135], v[38:41]
	v_mfma_f32_16x16x32_bf16 v[34:37], v[22:25], v[132:135], v[34:37]
	v_mfma_f32_16x16x32_bf16 v[38:41], v[26:29], v[136:139], v[38:41]
	v_mfma_f32_16x16x32_bf16 v[34:37], v[30:33], v[136:139], v[34:37]
	v_add_u32_e32 v180, 48, v50
	v_ashrrev_i32_e32 v181, 31, v180
	v_lshlrev_b64 v[178:179], 11, v[180:181]
	v_lshl_add_u64 v[178:179], v[54:55], 0, v[178:179]
	s_nop 7
	v_add_f32_e32 v62, v38, v175
	v_add_f32_e32 v63, v39, v175
	v_lshlrev_b32_e32 v64, 16, v152
	v_and_b32_e32 v65, 0xffff0000, v152
	v_mul_f32_e32 v62, v62, v64
	v_mul_f32_e32 v63, v63, v65
	v_lshlrev_b32_e32 v64, 16, v168
	v_and_b32_e32 v65, 0xffff0000, v168
	v_mul_f32_e32 v62, v62, v64
	v_mul_f32_e32 v63, v63, v65
	v_cvt_pk_bf16_f32 v58, v62, v63
	v_add_f32_e32 v62, v40, v175
	v_add_f32_e32 v63, v41, v175
	v_lshlrev_b32_e32 v64, 16, v153
	v_and_b32_e32 v65, 0xffff0000, v153
	v_mul_f32_e32 v62, v62, v64
	v_mul_f32_e32 v63, v63, v65
	v_lshlrev_b32_e32 v64, 16, v169
	v_and_b32_e32 v65, 0xffff0000, v169
	v_mul_f32_e32 v62, v62, v64
	v_mul_f32_e32 v63, v63, v65
	v_cvt_pk_bf16_f32 v59, v62, v63
	v_add_f32_e32 v62, v34, v175
	v_add_f32_e32 v63, v35, v175
	v_lshlrev_b32_e32 v64, 16, v154
	v_and_b32_e32 v65, 0xffff0000, v154
	v_mul_f32_e32 v62, v62, v64
	v_mul_f32_e32 v63, v63, v65
	v_lshlrev_b32_e32 v64, 16, v170
	v_and_b32_e32 v65, 0xffff0000, v170
	v_mul_f32_e32 v62, v62, v64
	v_mul_f32_e32 v63, v63, v65
	v_cvt_pk_bf16_f32 v60, v62, v63
	v_add_f32_e32 v62, v36, v175
	v_add_f32_e32 v63, v37, v175
	v_lshlrev_b32_e32 v64, 16, v155
	v_and_b32_e32 v65, 0xffff0000, v155
	v_mul_f32_e32 v62, v62, v64
	v_mul_f32_e32 v63, v63, v65
	v_lshlrev_b32_e32 v64, 16, v171
	v_and_b32_e32 v65, 0xffff0000, v171
	v_mul_f32_e32 v62, v62, v64
	v_mul_f32_e32 v63, v63, v65
	v_cvt_pk_bf16_f32 v61, v62, v63
	global_store_dwordx4 v[178:179], v[58:61], off
	global_load_dword v172, v[52:53], off offset:192
	v_add_u32_e32 v180, 64, v50
	v_mad_i64_i32 v[176:177], s[10:11], v180, s37, v[56:57]
	global_load_dwordx4 v[140:143], v[176:177], off
	global_load_dwordx4 v[156:159], v[176:177], off offset:2048
	global_load_dword v173, v[52:53], off offset:256
	v_add_u32_e32 v180, 80, v50
	v_mad_i64_i32 v[176:177], s[10:11], v180, s37, v[56:57]
	global_load_dwordx4 v[144:147], v[176:177], off
	global_load_dwordx4 v[160:163], v[176:177], off offset:2048
	global_load_dword v174, v[52:53], off offset:320
	v_add_u32_e32 v180, 96, v50
	v_mad_i64_i32 v[176:177], s[10:11], v180, s37, v[56:57]
	global_load_dwordx4 v[148:151], v[176:177], off
	global_load_dwordx4 v[164:167], v[176:177], off offset:2048
	global_load_dword v175, v[52:53], off offset:384
	v_add_u32_e32 v180, 112, v50
	v_mad_i64_i32 v[176:177], s[10:11], v180, s37, v[56:57]
	global_load_dwordx4 v[152:155], v[176:177], off
	global_load_dwordx4 v[168:171], v[176:177], off offset:2048
	ds_read_b128 v[76:79], v182 offset:16384
	ds_read_b128 v[80:83], v183 offset:16384
	ds_read_b128 v[84:87], v184 offset:16384
	ds_read_b128 v[88:91], v185 offset:16384
	ds_read_b128 v[92:95], v182 offset:20480
	ds_read_b128 v[96:99], v183 offset:20480
	ds_read_b128 v[100:103], v184 offset:20480
	ds_read_b128 v[104:107], v185 offset:20480
	ds_read_b128 v[108:111], v182 offset:24576
	ds_read_b128 v[112:115], v183 offset:24576
	ds_read_b128 v[116:119], v184 offset:24576
	ds_read_b128 v[120:123], v185 offset:24576
	ds_read_b128 v[124:127], v182 offset:28672
	ds_read_b128 v[128:131], v183 offset:28672
	ds_read_b128 v[132:135], v184 offset:28672
	ds_read_b128 v[136:139], v185 offset:28672
	s_waitcnt vmcnt(9) lgkmcnt(12)
	v_mfma_f32_16x16x32_bf16 v[38:41], v[2:5], v[76:79], 0
	v_mfma_f32_16x16x32_bf16 v[34:37], v[6:9], v[76:79], 0
	v_mfma_f32_16x16x32_bf16 v[38:41], v[10:13], v[80:83], v[38:41]
	v_mfma_f32_16x16x32_bf16 v[34:37], v[14:17], v[80:83], v[34:37]
	v_mfma_f32_16x16x32_bf16 v[38:41], v[18:21], v[84:87], v[38:41]
	v_mfma_f32_16x16x32_bf16 v[34:37], v[22:25], v[84:87], v[34:37]
	v_mfma_f32_16x16x32_bf16 v[38:41], v[26:29], v[88:91], v[38:41]
	v_mfma_f32_16x16x32_bf16 v[34:37], v[30:33], v[88:91], v[34:37]
	v_add_u32_e32 v180, 64, v50
	v_ashrrev_i32_e32 v181, 31, v180
	v_lshlrev_b64 v[178:179], 11, v[180:181]
	v_lshl_add_u64 v[178:179], v[54:55], 0, v[178:179]
	s_nop 7
	v_add_f32_e32 v62, v38, v172
	v_add_f32_e32 v63, v39, v172
	v_lshlrev_b32_e32 v64, 16, v140
	v_and_b32_e32 v65, 0xffff0000, v140
	v_mul_f32_e32 v62, v62, v64
	v_mul_f32_e32 v63, v63, v65
	v_lshlrev_b32_e32 v64, 16, v156
	v_and_b32_e32 v65, 0xffff0000, v156
	v_mul_f32_e32 v62, v62, v64
	v_mul_f32_e32 v63, v63, v65
	v_cvt_pk_bf16_f32 v58, v62, v63
	v_add_f32_e32 v62, v40, v172
	v_add_f32_e32 v63, v41, v172
	v_lshlrev_b32_e32 v64, 16, v141
	v_and_b32_e32 v65, 0xffff0000, v141
	v_mul_f32_e32 v62, v62, v64
	v_mul_f32_e32 v63, v63, v65
	v_lshlrev_b32_e32 v64, 16, v157
	v_and_b32_e32 v65, 0xffff0000, v157
	v_mul_f32_e32 v62, v62, v64
	v_mul_f32_e32 v63, v63, v65
	v_cvt_pk_bf16_f32 v59, v62, v63
	v_add_f32_e32 v62, v34, v172
	v_add_f32_e32 v63, v35, v172
	v_lshlrev_b32_e32 v64, 16, v142
	v_and_b32_e32 v65, 0xffff0000, v142
	v_mul_f32_e32 v62, v62, v64
	v_mul_f32_e32 v63, v63, v65
	v_lshlrev_b32_e32 v64, 16, v158
	v_and_b32_e32 v65, 0xffff0000, v158
	v_mul_f32_e32 v62, v62, v64
	v_mul_f32_e32 v63, v63, v65
	v_cvt_pk_bf16_f32 v60, v62, v63
	v_add_f32_e32 v62, v36, v172
	v_add_f32_e32 v63, v37, v172
	v_lshlrev_b32_e32 v64, 16, v143
	v_and_b32_e32 v65, 0xffff0000, v143
	v_mul_f32_e32 v62, v62, v64
	v_mul_f32_e32 v63, v63, v65
	v_lshlrev_b32_e32 v64, 16, v159
	v_and_b32_e32 v65, 0xffff0000, v159
	v_mul_f32_e32 v62, v62, v64
	v_mul_f32_e32 v63, v63, v65
	v_cvt_pk_bf16_f32 v61, v62, v63
	global_store_dwordx4 v[178:179], v[58:61], off
	s_waitcnt vmcnt(7) lgkmcnt(8)
	v_mfma_f32_16x16x32_bf16 v[38:41], v[2:5], v[92:95], 0
	v_mfma_f32_16x16x32_bf16 v[34:37], v[6:9], v[92:95], 0
	v_mfma_f32_16x16x32_bf16 v[38:41], v[10:13], v[96:99], v[38:41]
	v_mfma_f32_16x16x32_bf16 v[34:37], v[14:17], v[96:99], v[34:37]
	v_mfma_f32_16x16x32_bf16 v[38:41], v[18:21], v[100:103], v[38:41]
	v_mfma_f32_16x16x32_bf16 v[34:37], v[22:25], v[100:103], v[34:37]
	v_mfma_f32_16x16x32_bf16 v[38:41], v[26:29], v[104:107], v[38:41]
	v_mfma_f32_16x16x32_bf16 v[34:37], v[30:33], v[104:107], v[34:37]
	v_add_u32_e32 v180, 80, v50
	v_ashrrev_i32_e32 v181, 31, v180
	v_lshlrev_b64 v[178:179], 11, v[180:181]
	v_lshl_add_u64 v[178:179], v[54:55], 0, v[178:179]
	s_nop 7
	v_add_f32_e32 v62, v38, v173
	v_add_f32_e32 v63, v39, v173
	v_lshlrev_b32_e32 v64, 16, v144
	v_and_b32_e32 v65, 0xffff0000, v144
	v_mul_f32_e32 v62, v62, v64
	v_mul_f32_e32 v63, v63, v65
	v_lshlrev_b32_e32 v64, 16, v160
	v_and_b32_e32 v65, 0xffff0000, v160
	v_mul_f32_e32 v62, v62, v64
	v_mul_f32_e32 v63, v63, v65
	v_cvt_pk_bf16_f32 v58, v62, v63
	v_add_f32_e32 v62, v40, v173
	v_add_f32_e32 v63, v41, v173
	v_lshlrev_b32_e32 v64, 16, v145
	v_and_b32_e32 v65, 0xffff0000, v145
	v_mul_f32_e32 v62, v62, v64
	v_mul_f32_e32 v63, v63, v65
	v_lshlrev_b32_e32 v64, 16, v161
	v_and_b32_e32 v65, 0xffff0000, v161
	v_mul_f32_e32 v62, v62, v64
	v_mul_f32_e32 v63, v63, v65
	v_cvt_pk_bf16_f32 v59, v62, v63
	v_add_f32_e32 v62, v34, v173
	v_add_f32_e32 v63, v35, v173
	v_lshlrev_b32_e32 v64, 16, v146
	v_and_b32_e32 v65, 0xffff0000, v146
	v_mul_f32_e32 v62, v62, v64
	v_mul_f32_e32 v63, v63, v65
	v_lshlrev_b32_e32 v64, 16, v162
	v_and_b32_e32 v65, 0xffff0000, v162
	v_mul_f32_e32 v62, v62, v64
	v_mul_f32_e32 v63, v63, v65
	v_cvt_pk_bf16_f32 v60, v62, v63
	v_add_f32_e32 v62, v36, v173
	v_add_f32_e32 v63, v37, v173
	v_lshlrev_b32_e32 v64, 16, v147
	v_and_b32_e32 v65, 0xffff0000, v147
	v_mul_f32_e32 v62, v62, v64
	v_mul_f32_e32 v63, v63, v65
	v_lshlrev_b32_e32 v64, 16, v163
	v_and_b32_e32 v65, 0xffff0000, v163
	v_mul_f32_e32 v62, v62, v64
	v_mul_f32_e32 v63, v63, v65
	v_cvt_pk_bf16_f32 v61, v62, v63
	global_store_dwordx4 v[178:179], v[58:61], off
	s_waitcnt vmcnt(5) lgkmcnt(4)
	v_mfma_f32_16x16x32_bf16 v[38:41], v[2:5], v[108:111], 0
	v_mfma_f32_16x16x32_bf16 v[34:37], v[6:9], v[108:111], 0
	v_mfma_f32_16x16x32_bf16 v[38:41], v[10:13], v[112:115], v[38:41]
	v_mfma_f32_16x16x32_bf16 v[34:37], v[14:17], v[112:115], v[34:37]
	v_mfma_f32_16x16x32_bf16 v[38:41], v[18:21], v[116:119], v[38:41]
	v_mfma_f32_16x16x32_bf16 v[34:37], v[22:25], v[116:119], v[34:37]
	v_mfma_f32_16x16x32_bf16 v[38:41], v[26:29], v[120:123], v[38:41]
	v_mfma_f32_16x16x32_bf16 v[34:37], v[30:33], v[120:123], v[34:37]
	v_add_u32_e32 v180, 96, v50
	v_ashrrev_i32_e32 v181, 31, v180
	v_lshlrev_b64 v[178:179], 11, v[180:181]
	v_lshl_add_u64 v[178:179], v[54:55], 0, v[178:179]
	s_nop 7
	v_add_f32_e32 v62, v38, v174
	v_add_f32_e32 v63, v39, v174
	v_lshlrev_b32_e32 v64, 16, v148
	v_and_b32_e32 v65, 0xffff0000, v148
	v_mul_f32_e32 v62, v62, v64
	v_mul_f32_e32 v63, v63, v65
	v_lshlrev_b32_e32 v64, 16, v164
	v_and_b32_e32 v65, 0xffff0000, v164
	v_mul_f32_e32 v62, v62, v64
	v_mul_f32_e32 v63, v63, v65
	v_cvt_pk_bf16_f32 v58, v62, v63
	v_add_f32_e32 v62, v40, v174
	v_add_f32_e32 v63, v41, v174
	v_lshlrev_b32_e32 v64, 16, v149
	v_and_b32_e32 v65, 0xffff0000, v149
	v_mul_f32_e32 v62, v62, v64
	v_mul_f32_e32 v63, v63, v65
	v_lshlrev_b32_e32 v64, 16, v165
	v_and_b32_e32 v65, 0xffff0000, v165
	v_mul_f32_e32 v62, v62, v64
	v_mul_f32_e32 v63, v63, v65
	v_cvt_pk_bf16_f32 v59, v62, v63
	v_add_f32_e32 v62, v34, v174
	v_add_f32_e32 v63, v35, v174
	v_lshlrev_b32_e32 v64, 16, v150
	v_and_b32_e32 v65, 0xffff0000, v150
	v_mul_f32_e32 v62, v62, v64
	v_mul_f32_e32 v63, v63, v65
	v_lshlrev_b32_e32 v64, 16, v166
	v_and_b32_e32 v65, 0xffff0000, v166
	v_mul_f32_e32 v62, v62, v64
	v_mul_f32_e32 v63, v63, v65
	v_cvt_pk_bf16_f32 v60, v62, v63
	v_add_f32_e32 v62, v36, v174
	v_add_f32_e32 v63, v37, v174
	v_lshlrev_b32_e32 v64, 16, v151
	v_and_b32_e32 v65, 0xffff0000, v151
	v_mul_f32_e32 v62, v62, v64
	v_mul_f32_e32 v63, v63, v65
	v_lshlrev_b32_e32 v64, 16, v167
	v_and_b32_e32 v65, 0xffff0000, v167
	v_mul_f32_e32 v62, v62, v64
	v_mul_f32_e32 v63, v63, v65
	v_cvt_pk_bf16_f32 v61, v62, v63
	global_store_dwordx4 v[178:179], v[58:61], off
	s_waitcnt vmcnt(3) lgkmcnt(0)
	v_mfma_f32_16x16x32_bf16 v[38:41], v[2:5], v[124:127], 0
	v_mfma_f32_16x16x32_bf16 v[34:37], v[6:9], v[124:127], 0
	v_mfma_f32_16x16x32_bf16 v[38:41], v[10:13], v[128:131], v[38:41]
	v_mfma_f32_16x16x32_bf16 v[34:37], v[14:17], v[128:131], v[34:37]
	v_mfma_f32_16x16x32_bf16 v[38:41], v[18:21], v[132:135], v[38:41]
	v_mfma_f32_16x16x32_bf16 v[34:37], v[22:25], v[132:135], v[34:37]
	v_mfma_f32_16x16x32_bf16 v[38:41], v[26:29], v[136:139], v[38:41]
	v_mfma_f32_16x16x32_bf16 v[34:37], v[30:33], v[136:139], v[34:37]
	v_add_u32_e32 v180, 112, v50
	v_ashrrev_i32_e32 v181, 31, v180
	v_lshlrev_b64 v[178:179], 11, v[180:181]
	v_lshl_add_u64 v[178:179], v[54:55], 0, v[178:179]
	s_nop 7
	v_add_f32_e32 v62, v38, v175
	v_add_f32_e32 v63, v39, v175
	v_lshlrev_b32_e32 v64, 16, v152
	v_and_b32_e32 v65, 0xffff0000, v152
	v_mul_f32_e32 v62, v62, v64
	v_mul_f32_e32 v63, v63, v65
	v_lshlrev_b32_e32 v64, 16, v168
	v_and_b32_e32 v65, 0xffff0000, v168
	v_mul_f32_e32 v62, v62, v64
	v_mul_f32_e32 v63, v63, v65
	v_cvt_pk_bf16_f32 v58, v62, v63
	v_add_f32_e32 v62, v40, v175
	v_add_f32_e32 v63, v41, v175
	v_lshlrev_b32_e32 v64, 16, v153
	v_and_b32_e32 v65, 0xffff0000, v153
	v_mul_f32_e32 v62, v62, v64
	v_mul_f32_e32 v63, v63, v65
	v_lshlrev_b32_e32 v64, 16, v169
	v_and_b32_e32 v65, 0xffff0000, v169
	v_mul_f32_e32 v62, v62, v64
	v_mul_f32_e32 v63, v63, v65
	v_cvt_pk_bf16_f32 v59, v62, v63
	v_add_f32_e32 v62, v34, v175
	v_add_f32_e32 v63, v35, v175
	v_lshlrev_b32_e32 v64, 16, v154
	v_and_b32_e32 v65, 0xffff0000, v154
	v_mul_f32_e32 v62, v62, v64
	v_mul_f32_e32 v63, v63, v65
	v_lshlrev_b32_e32 v64, 16, v170
	v_and_b32_e32 v65, 0xffff0000, v170
	v_mul_f32_e32 v62, v62, v64
	v_mul_f32_e32 v63, v63, v65
	v_cvt_pk_bf16_f32 v60, v62, v63
	v_add_f32_e32 v62, v36, v175
	v_add_f32_e32 v63, v37, v175
	v_lshlrev_b32_e32 v64, 16, v155
	v_and_b32_e32 v65, 0xffff0000, v155
	v_mul_f32_e32 v62, v62, v64
	v_mul_f32_e32 v63, v63, v65
	v_lshlrev_b32_e32 v64, 16, v171
	v_and_b32_e32 v65, 0xffff0000, v171
	v_mul_f32_e32 v62, v62, v64
	v_mul_f32_e32 v63, v63, v65
	v_cvt_pk_bf16_f32 v61, v62, v63
	global_store_dwordx4 v[178:179], v[58:61], off
	s_add_i32 s8, s8, s88
	s_add_i32 s7, s7, s13
	s_cmp_ge_i32 s8, s4
	s_cbranch_scc0 .LBB0_274
